# grid barrier: completing workgroup releases all XCD generation words directly (one hop less)
# speedup vs baseline: 1.0586x; 1.0063x over previous
.LBB0_701:
	s_or_b64 exec, exec, s[0:1]
	s_waitcnt vmcnt(0)
	s_branch .LBB0_702
.Lbar_last:
	s_or_b64 exec, exec, s[0:1]
	s_add_u32 s4, s18, 0x2400
	s_addc_u32 s5, s19, 0
	global_atomic_add v153, v185, s[4:5]
	global_atomic_add v153, v185, s[4:5] offset:256
	global_atomic_add v153, v185, s[4:5] offset:512
	global_atomic_add v153, v185, s[4:5] offset:768
	global_atomic_add v153, v185, s[4:5] offset:1024
	global_atomic_add v153, v185, s[4:5] offset:1280
	global_atomic_add v153, v185, s[4:5] offset:1536
	global_atomic_add v153, v185, s[4:5] offset:1792
	global_atomic_add v153, v185, s[4:5] offset:2048
	global_atomic_add v153, v185, s[4:5] offset:2304
	global_atomic_add v153, v185, s[4:5] offset:2560
	global_atomic_add v153, v185, s[4:5] offset:2816
	global_atomic_add v153, v185, s[4:5] offset:3072
	global_atomic_add v153, v185, s[4:5] offset:3328
	global_atomic_add v153, v185, s[4:5] offset:3584
	global_atomic_add v153, v185, s[4:5] offset:3840
	global_atomic_add v[0:1], v185, off
	s_waitcnt vmcnt(0)
	s_branch .LBB0_702
